# sample attention phase: item-less waves stream this CU's K/V cache lines once (one dword per line) ahead of the consumer waves
# baseline (speedup 1.0000x reference)
; DI bf16x8 ld8f_bf(const float* p) { const f32x4 a = *(const f32x4*)p, b = *(const f32x4*)(p + 4); return __builtin_bit_cast(bf16x8, pack8(a, b)); }
;     DI bf16x8 kfrag_t(int tl, int kk) const { const int lane = threadIdx.x & 63; return ld8f_bf(krow(ck, nk, 32 * tl + (lane & 31)) + 16 * kk + 8 * (lane >> 5)); }
; #define REPS(k) for (int rep_ = 0, nrep_ = 1 + ((DUP_MASK >> (k)) & 1); rep_ < nrep_; ++rep_)
; #define ATT_Q_RESET() do { __syncthreads(); if (tid == 0) *qctr = 0u; __syncthreads(); } while (0)
; #define ATT_Q_NEXT() __builtin_amdgcn_readfirstlane(lane == 0 ? (int)__hip_atomic_fetch_add(qctr, 1u, __ATOMIC_RELAXED, __HIP_MEMORY_SCOPE_WORKGROUP) : 0)
;     DI bf16x8 kfrag_t(int tl, int kk) const { const int lane = threadIdx.x & 63; return ld8f_bf(mk + ((size_t)(b * 256 + 32 * tl + (lane & 31)) * 4 + hd) * 128 + 16 * kk + 8 * (lane >> 5)); }
;     DI bf16x8 vfrag_t(int tl, int s2, int dd) const { const int lane = threadIdx.x & 63; const float* p = mv + ((size_t)(b * 256 + 32 * tl + 16 * s2 + 4 * (lane >> 5)) * 4 + hd) * 128 + 32 * dd + (lane & 31); f32x4 a, c;
; #pragma unroll
;         for (int j = 0; j < 4; ++j) { a[j] = p[(size_t)j * 512]; c[j] = p[(size_t)(8 + j) * 512]; }
; __global__ void __launch_bounds__(512, 2) fwd_kernel(Params P) {
;     ...
;     if (IN(2)) REPS(2) {
;         for (int it = cu; it < 512; it += G) { hgrn_item<false>(lds, PROJ, HST, HDV, P.in[I_HNW], it, DRY); __syncthreads(); }
;         for (int it = cu; it < 512; it += G) hgrn_sample_item(lds, PROJ, P.in[I_ST], P.out, P.in[I_HNW], it, DRY);
;         ATT_Q_RESET();
;         for (int it = ATT_Q_NEXT() * G + cu; it < 768; it = ATT_Q_NEXT() * G + cu) {
;             if (it < 512) { AttMemS t{PROJ, P.in[I_CMK], P.in[I_CMV], it >> 2, it & 3, DRY}; attn_item(t); }
;             else { const int r = it - 512; AttSwS t{PROJ, P.in[I_CK], P.in[I_CV], P.out + O_KWS, P.out + O_VWS, P.in[I_SINK], r >> 1, r & 1, DRY}; attn_item(t); }
.LBB0_864:
	s_mov_b64 s[26:27], exec
	v_mbcnt_lo_u32_b32 v2, s26, 0
	v_mbcnt_hi_u32_b32 v2, s27, v2
	v_cmp_eq_u32_e32 vcc, 0, v2
	s_and_saveexec_b64 s[18:19], vcc
	s_cbranch_execz .LBB0_847
	s_bcnt1_i32_b64 s8, s[26:27]
	v_mov_b32_e32 v3, s38
	v_mov_b32_e32 v4, s8
	ds_add_rtn_u32 v3, v3, v4
	s_branch .LBB0_847
	s_branch .LBB0_866
.Lpf_entry:
	s_sub_i32 s28, s39, 0x300
	s_cmpk_gt_i32 s28, 0x2ff
	s_cbranch_scc1 .LBB0_866
	v_lshrrev_b32_e32 v130, 1, v182
	v_and_b32_e32 v131, 1, v182
	s_cmpk_gt_i32 s28, 0x1ff
	s_cbranch_scc1 .Lpf_sw
	s_load_dwordx2 s[30:31], s[0:1], 0x28
	s_load_dwordx2 s[32:33], s[0:1], 0x30
	s_lshr_b32 s29, s28, 2
	s_and_b32 s37, s28, 3
	s_lshl_b32 s29, s29, 19
	s_lshl_b32 s37, s37, 9
	s_add_u32 s29, s29, s37
	v_lshlrev_b32_e32 v130, 11, v130
	v_lshl_add_u32 v130, v131, 7, v130
	v_add_u32_e32 v130, s29, v130
	s_movk_i32 s36, 8
	s_waitcnt lgkmcnt(0)
.Lpf_mloop:
	global_load_dword v132, v130, s[30:31]
	global_load_dword v133, v130, s[30:31] offset:256
	global_load_dword v134, v130, s[32:33]
	global_load_dword v135, v130, s[32:33] offset:256
	v_add_u32_e32 v130, 0x10000, v130
	s_sub_u32 s36, s36, 1
	s_waitcnt vmcnt(4)
	s_cmp_lg_u32 s36, 0
	s_cbranch_scc1 .Lpf_mloop
	s_waitcnt vmcnt(0)
	s_branch .LBB0_866
.Lpf_sw:
	s_load_dwordx4 s[32:35], s[0:1], 0x10
	s_sub_i32 s28, s28, 0x200
	s_lshr_b32 s29, s28, 1
	s_and_b32 s37, s28, 1
	s_lshl_b32 s29, s29, 16
	s_lshl_b32 s37, s37, 8
	s_add_u32 s29, s29, s37
	v_lshlrev_b32_e32 v130, 9, v130
	v_lshl_add_u32 v130, v131, 7, v130
	v_add_u32_e32 v130, s29, v130
	s_movk_i32 s36, 4
	s_waitcnt lgkmcnt(0)
.Lpf_sloop:
	global_load_dword v132, v130, s[32:33]
	global_load_dword v133, v130, s[34:35]
	v_add_u32_e32 v130, 0x4000, v130
	s_sub_u32 s36, s36, 1
	s_cmp_lg_u32 s36, 0
	s_cbranch_scc1 .Lpf_sloop
	s_waitcnt vmcnt(0)
